# FoX key loop: packed row-sum adds between the PV MFMAs replaced by running partial sums behind each exp (instruction selection: no packed f32 ops beside MFMAs)
# baseline (speedup 1.0000x reference)
; DI float bf_lo(unsigned u) { return __uint_as_float(u << 16); }
; DI float bf_hi(unsigned u) { return __uint_as_float(u & 0xffff0000u); }
;     ...
;     if (FOX) {
;         float q2 = 0.f;
; #pragma unroll
;         for (int ks = 0; ks < 4; ++ks) {
;             const u32x4 w = __builtin_bit_cast(u32x4, qf[ks]);
; #pragma unroll
;             for (int e = 0; e < 4; ++e) { const float a = bf_lo(w[e]), b2 = bf_hi(w[e]); q2 += a * a + b2 * b2; }
;         }
;         { const auto sw = __builtin_amdgcn_permlane32_swap(__float_as_uint(q2), __float_as_uint(q2), false, false);
;           q2 = __uint_as_float(sw[0]) + __uint_as_float(sw[1]); }
;         qkb = sqrtf(q2 * kmax2) * 1.01f + 0.01f;
;     }
;     constexpr int NK2 = (64 * KCH + NT - 1) / NT;
;     u32x4 kr[NK2]; u32x4 vr; float br = 0.f;
;     auto gload = [&](int j) {
; #pragma unroll
;         for (int r = 0; r < NK2; ++r) {
;             const int c = tid + NT * r;
;             if (c < 64 * KCH) { const int row = c / KCH, ch = c - row * KCH; kr[r] = *(const u32x4*)(kbase + (size_t)(64 * j + row) * ldk + ch * 8); }
;         }
;         { const int row = tid >> 3, ch = tid & 7; vr = *(const u32x4*)(vt + (size_t)row * LP + 64 * j + ch * 8); }
;         if (FOX) { if (tid < 64) br = bias[64 * j + tid]; }
;     };
;     auto lstore = [&](int st) {
;         unsigned char* base = lds + st * STG;
; #pragma unroll
;         for (int r = 0; r < NK2; ++r) {
;             const int c = tid + NT * r;
;             if (c < 64 * KCH) { const int row = c / KCH, ch = c - row * KCH; *(u32x4*)(base + row * KROW + ch * 16) = kr[r]; }
;         }
;         { const int row = tid >> 3, ch = tid & 7; unsigned char* d = base + KBYTES + row * VROW + ch * 16;
;           *(u32x2*)d = (u32x2){vr[0], vr[1]}; *(u32x2*)(d + 8) = (u32x2){vr[2], vr[3]}; }
;         if (FOX) { if (tid < 64) *(float*)(base + KBYTES + VBYTES + tid * 4) = br; }
;     };
;     const int jlast = nkt - 1;
;     gload(jlast); lstore(0);
;     __syncthreads();
;     m = -1e30f;
.LBB0_787:
	s_or_b64 exec, exec, s[18:19]
	v_add3_u32 v6, v170, v191, s87
	s_waitcnt vmcnt(0)
	ds_write2_b64 v6, v[100:101], v[102:103] offset1:1
	s_and_saveexec_b64 s[18:19], s[8:9]
	v_add_u32_e32 v6, 0, v171
	ds_write_b32 v6, v130 offset:19968
	s_or_b64 exec, exec, s[18:19]
	s_cmp_gt_i32 s93, 16
	s_waitcnt lgkmcnt(0)
	s_barrier
	s_cbranch_scc1 .LBB0_820
	v_add_f32_e32 v4, v4, v5
	v_mul_f32_e32 v1, v1, v4
	s_mov_b32 s2, 0xf800000
	v_mul_f32_e32 v4, 0x4f800000, v1
	v_cmp_gt_f32_e32 vcc, s2, v1
	v_lshl_add_u64 v[124:125], v[140:141], 1, v[2:3]
	s_ashr_i32 s71, s22, 6
	v_cndmask_b32_e32 v1, v1, v4, vcc
	v_sqrt_f32_e32 v4, v1
	v_mov_b32_e32 v14, v0
	v_mov_b32_e32 v15, v0
	v_mov_b32_e32 v5, v0
	v_add_u32_e32 v2, -1, v4
	v_fma_f32 v3, -v2, v4, v1
	v_cmp_ge_f32_e64 s[18:19], 0, v3
	v_add_u32_e32 v3, 1, v4
	v_mov_b32_e32 v6, v0
	v_cndmask_b32_e64 v2, v4, v2, s[18:19]
	v_fma_f32 v4, -v3, v4, v1
	v_cmp_lt_f32_e64 s[18:19], 0, v4
	v_mov_b32_e32 v4, v0
	v_mov_b32_e32 v7, v0
	v_cndmask_b32_e64 v2, v2, v3, s[18:19]
	v_mul_f32_e32 v3, 0x37800000, v2
	v_cndmask_b32_e32 v2, v2, v3, vcc
	v_cmp_class_f32_e32 vcc, v1, v204
	s_max_i32 s18, s71, 0
	s_lshl_b32 s60, s18, 6
	v_cndmask_b32_e32 v1, v2, v1, vcc
	v_fmamk_f32 v156, v1, 0x3f8147ae, v205
	v_subrev_u32_e32 v1, s70, v178
	s_lshl_b32 s18, s93, 8
	v_subrev_u32_e32 v135, s18, v1
	v_mov_b32_e32 v1, v0
	v_mov_b32_e32 v2, v0
	v_mov_b32_e32 v3, v0
	v_mov_b32_e32 v8, v0
	v_mov_b32_e32 v9, v0
	v_mov_b32_e32 v10, v0
	v_mov_b32_e32 v11, v0
	v_mov_b32_e32 v12, v0
	v_mov_b32_e32 v13, v0
	v_mov_b64_e32 v[46:47], v[14:15]
	v_mov_b64_e32 v[30:31], v[14:15]
	s_mov_b32 s2, 0
	v_lshl_add_u64 v[126:127], v[150:151], 1, s[20:21]
	v_add_u32_e32 v131, 31, v209
	v_add_u32_e32 v133, s70, v176
	v_add_u32_e32 v134, s70, v177
	s_mov_b64 s[74:75], 0
	v_mov_b32_e32 v132, 0
	v_mov_b32_e32 v248, 0
	v_mov_b32_e32 v249, 0
	v_mov_b32_e32 v250, 0
	v_mov_b32_e32 v251, 0
	v_mov_b32_e32 v252, 0
	v_mov_b32_e32 v253, 0
	v_mov_b32_e32 v254, 0
	v_mov_b32_e32 v255, 0
	v_mov_b32_e32 v129, 0xf149f2ca
	v_mov_b64_e32 v[44:45], v[12:13]
	v_mov_b64_e32 v[42:43], v[10:11]
	v_mov_b64_e32 v[40:41], v[8:9]
	v_mov_b64_e32 v[38:39], v[6:7]
	v_mov_b64_e32 v[36:37], v[4:5]
	v_mov_b64_e32 v[34:35], v[2:3]
	v_mov_b64_e32 v[32:33], v[0:1]
	v_mov_b64_e32 v[28:29], v[12:13]
	v_mov_b64_e32 v[26:27], v[10:11]
	v_mov_b64_e32 v[24:25], v[8:9]
	v_mov_b64_e32 v[22:23], v[6:7]
	v_mov_b64_e32 v[20:21], v[4:5]
	v_mov_b64_e32 v[18:19], v[2:3]
	v_mov_b64_e32 v[16:17], v[0:1]
	s_mov_b32 s61, 0
	s_branch .LBB0_792

;     ...
;             float mxa[2];
; #pragma unroll
;             for (int t2 = 0; t2 < 2; ++t2) {
;                 float x0 = fmaxf(fmaxf(s[t2][0], s[t2][1]), s[t2][2]);
;                 float x1 = fmaxf(fmaxf(s[t2][3], s[t2][4]), s[t2][5]);
;                 float x2 = fmaxf(fmaxf(s[t2][6], s[t2][7]), s[t2][8]);
;                 float x3 = fmaxf(fmaxf(s[t2][9], s[t2][10]), s[t2][11]);
;                 float x4 = fmaxf(fmaxf(s[t2][12], s[t2][13]), s[t2][14]);
;                 mxa[t2] = fmaxf(fmaxf(fmaxf(x0, x1), x2), fmaxf(fmaxf(x3, x4), s[t2][15]));
;             }
;             float mx = fmaxf(mxa[0], mxa[1]);
;             { const auto sw = __builtin_amdgcn_permlane32_swap(__float_as_uint(mx), __float_as_uint(mx), false, false);
;               mx = fmaxf(__uint_as_float(sw[0]), __uint_as_float(sw[1])); }
;             if (__builtin_amdgcn_ballot_w64(mx > m + 8.0f) != 0ull) {
;                 const float mn = fmaxf(m, mx);
;                 const float alpha = __builtin_amdgcn_exp2f(m - mn);
;                 m = mn;
;                 lsum *= alpha;
; #pragma unroll
;                 for (int d = 0; d < 2; ++d)
; #pragma unroll
;                     for (int r = 0; r < 16; ++r) o[d][r] *= alpha;
;             }
;             float ps0 = 0.f, ps1 = 0.f, ps2 = 0.f, ps3 = 0.f;
; #pragma unroll
;             for (int t2 = 0; t2 < 2; ++t2)
; #pragma unroll
;                 for (int r = 0; r < 16; r += 4) {
;                     const float e0 = __builtin_amdgcn_exp2f(s[t2][r] - m), e1 = __builtin_amdgcn_exp2f(s[t2][r + 1] - m);
;                     const float e2 = __builtin_amdgcn_exp2f(s[t2][r + 2] - m), e3 = __builtin_amdgcn_exp2f(s[t2][r + 3] - m);
;                     s[t2][r] = e0; s[t2][r + 1] = e1; s[t2][r + 2] = e2; s[t2][r + 3] = e3;
;                     ps0 += e0; ps1 += e1; ps2 += e2; ps3 += e3;
;                 }
;             lsum += (ps0 + ps1) + (ps2 + ps3);
; #pragma unroll
;             for (int kk = 0; kk < 4; ++kk) {
;                 const int t2 = kk >> 1, s8 = (kk & 1) * 8;
;                 u32x4 pw;
;                 pw[0] = pk2(s[t2][s8 + 0], s[t2][s8 + 1]); pw[1] = pk2(s[t2][s8 + 2], s[t2][s8 + 3]);
;                 pw[2] = pk2(s[t2][s8 + 4], s[t2][s8 + 5]); pw[3] = pk2(s[t2][s8 + 6], s[t2][s8 + 7]);
;                 const bf16x8 pf = __builtin_bit_cast(bf16x8, pw);
; #pragma unroll
.LBB0_814:
	s_or_b64 exec, exec, s[82:83]
	v_max3_f32 v1, v64, v65, v66
	v_max3_f32 v14, v67, v68, v69
	v_max3_f32 v15, v70, v71, v72
	v_max3_f32 v128, v73, v74, v75
	v_max3_f32 v158, v76, v77, v78
	v_max3_f32 v1, v1, v14, v15
	v_max3_f32 v14, v128, v158, v79
	v_max_f32_e32 v15, v49, v49
	v_max_f32_e32 v128, v48, v48
	v_max_f32_e32 v15, v128, v15
	v_max3_f32 v128, v51, v52, v53
	v_max3_f32 v159, v57, v58, v59
	v_max3_f32 v160, v60, v61, v62
	v_max3_f32 v158, v54, v55, v56
	v_max3_f32 v15, v15, v50, v128
	v_max3_f32 v128, v159, v160, v63
	v_max3_f32 v15, v15, v158, v128
	v_max3_f32 v1, v1, v14, v15
	v_mov_b32_e32 v14, v1
	s_nop 1
	v_permlane32_swap_b32_e32 v1, v14
	v_max_f32_e32 v14, v14, v14
	v_max_f32_e32 v1, v1, v1
	v_max_f32_e32 v1, v1, v14
	v_add_f32_e32 v14, 0x41000000, v129
	v_cmp_gt_f32_e32 vcc, v1, v14
	s_cbranch_vccz .LBB0_816
	v_max_f32_e32 v1, v1, v1
	v_max_f32_e32 v14, v129, v129
	v_max_f32_e32 v1, v14, v1
	v_sub_f32_e32 v14, v129, v1
	v_exp_f32_e32 v14, v14
	v_mov_b32_e32 v129, v1
	v_pk_mul_f32 v[46:47], v[46:47], v[14:15] op_sel_hi:[1,0]
	v_pk_mul_f32 v[44:45], v[44:45], v[14:15] op_sel_hi:[1,0]
	v_pk_mul_f32 v[42:43], v[42:43], v[14:15] op_sel_hi:[1,0]
	v_pk_mul_f32 v[40:41], v[40:41], v[14:15] op_sel_hi:[1,0]
	v_pk_mul_f32 v[38:39], v[38:39], v[14:15] op_sel_hi:[1,0]
	v_pk_mul_f32 v[36:37], v[36:37], v[14:15] op_sel_hi:[1,0]
	v_pk_mul_f32 v[34:35], v[34:35], v[14:15] op_sel_hi:[1,0]
	v_pk_mul_f32 v[32:33], v[32:33], v[14:15] op_sel_hi:[1,0]
	v_pk_mul_f32 v[30:31], v[30:31], v[14:15] op_sel_hi:[1,0]
	v_pk_mul_f32 v[28:29], v[28:29], v[14:15] op_sel_hi:[1,0]
	v_pk_mul_f32 v[26:27], v[26:27], v[14:15] op_sel_hi:[1,0]
	v_pk_mul_f32 v[24:25], v[24:25], v[14:15] op_sel_hi:[1,0]
	v_pk_mul_f32 v[22:23], v[22:23], v[14:15] op_sel_hi:[1,0]
	v_pk_mul_f32 v[20:21], v[20:21], v[14:15] op_sel_hi:[1,0]
	v_pk_mul_f32 v[18:19], v[18:19], v[14:15] op_sel_hi:[1,0]
	v_pk_mul_f32 v[16:17], v[16:17], v[14:15] op_sel_hi:[1,0]
	v_mul_f32_e32 v248, v248, v14
	v_mul_f32_e32 v249, v249, v14
	v_mul_f32_e32 v250, v250, v14
	v_mul_f32_e32 v251, v251, v14
	v_mul_f32_e32 v252, v252, v14
	v_mul_f32_e32 v253, v253, v14
	v_mul_f32_e32 v254, v254, v14
	v_mul_f32_e32 v255, v255, v14
.LBB0_816:
	v_sub_f32_e32 v1, v64, v129
	v_exp_f32_e32 v14, v1
	v_sub_f32_e32 v1, v65, v129
	v_add_f32_e32 v248, v248, v14
	v_exp_f32_e32 v64, v1
	v_sub_f32_e32 v1, v66, v129
	v_add_f32_e32 v249, v249, v64
	v_exp_f32_e32 v15, v1
	v_sub_f32_e32 v1, v67, v129
	v_add_f32_e32 v250, v250, v15
	v_exp_f32_e32 v65, v1
	v_sub_f32_e32 v1, v68, v129
	v_add_f32_e32 v251, v251, v65
	v_exp_f32_e32 v66, v1
	v_sub_f32_e32 v1, v69, v129
	v_add_f32_e32 v252, v252, v66
	v_exp_f32_e32 v68, v1
	v_sub_f32_e32 v1, v70, v129
	v_add_f32_e32 v253, v253, v68
	v_exp_f32_e32 v67, v1
	v_sub_f32_e32 v1, v71, v129
	v_add_f32_e32 v254, v254, v67
	v_exp_f32_e32 v69, v1
	v_sub_f32_e32 v1, v72, v129
	v_add_f32_e32 v255, v255, v69
	v_exp_f32_e32 v70, v1
	v_sub_f32_e32 v1, v73, v129
	v_add_f32_e32 v248, v248, v70
	v_exp_f32_e32 v72, v1
	v_sub_f32_e32 v1, v74, v129
	v_add_f32_e32 v249, v249, v72
	v_exp_f32_e32 v71, v1
	v_sub_f32_e32 v1, v75, v129
	v_add_f32_e32 v250, v250, v71
	v_exp_f32_e32 v73, v1
	v_sub_f32_e32 v1, v76, v129
	v_add_f32_e32 v251, v251, v73
	v_exp_f32_e32 v74, v1
	v_sub_f32_e32 v1, v77, v129
	v_add_f32_e32 v252, v252, v74
	v_exp_f32_e32 v76, v1
	v_sub_f32_e32 v1, v78, v129
	v_add_f32_e32 v253, v253, v76
	v_exp_f32_e32 v75, v1
	v_sub_f32_e32 v1, v79, v129
	v_add_f32_e32 v254, v254, v75
	v_exp_f32_e32 v77, v1
	v_sub_f32_e32 v1, v48, v129
	v_add_f32_e32 v255, v255, v77
	v_exp_f32_e32 v78, v1
	v_sub_f32_e32 v1, v49, v129
	v_add_f32_e32 v248, v248, v78
	v_exp_f32_e32 v158, v1
	v_sub_f32_e32 v1, v50, v129
	v_add_f32_e32 v249, v249, v158
	v_exp_f32_e32 v79, v1
	v_sub_f32_e32 v1, v51, v129
	v_add_f32_e32 v250, v250, v79
	v_cvt_pk_bf16_f32 v48, v14, v64
	v_cvt_pk_bf16_f32 v49, v15, v65
	v_cvt_pk_bf16_f32 v50, v66, v68
	v_cvt_pk_bf16_f32 v51, v67, v69
	v_exp_f32_e32 v159, v1
	v_sub_f32_e32 v1, v52, v129
	v_add_f32_e32 v251, v251, v159
	s_waitcnt lgkmcnt(7)
	v_mfma_f32_32x32x16_bf16 v[32:47], v[120:123], v[48:51], v[32:47]
	v_exp_f32_e32 v52, v1
	v_sub_f32_e32 v1, v53, v129
	v_add_f32_e32 v252, v252, v52
	v_exp_f32_e32 v160, v1
	v_sub_f32_e32 v1, v54, v129
	v_add_f32_e32 v253, v253, v160
	v_exp_f32_e32 v53, v1
	v_sub_f32_e32 v1, v55, v129
	v_add_f32_e32 v254, v254, v53
	v_exp_f32_e32 v161, v1
	s_waitcnt lgkmcnt(5)
	v_add_f32_e32 v255, v255, v161
	v_mfma_f32_32x32x16_bf16 v[16:31], v[116:119], v[48:51], v[16:31]
	v_cvt_pk_bf16_f32 v48, v70, v72
	v_cvt_pk_bf16_f32 v49, v71, v73
	v_cvt_pk_bf16_f32 v50, v74, v76
	v_cvt_pk_bf16_f32 v51, v75, v77
	v_sub_f32_e32 v1, v56, v129
	v_exp_f32_e32 v54, v1
	v_sub_f32_e32 v1, v57, v129
	v_add_f32_e32 v248, v248, v54
	v_mfma_f32_32x32x16_bf16 v[32:47], v[112:115], v[48:51], v[32:47]
	v_exp_f32_e32 v56, v1
	v_sub_f32_e32 v1, v58, v129
	v_add_f32_e32 v249, v249, v56
	v_exp_f32_e32 v55, v1
	v_sub_f32_e32 v1, v59, v129
	v_add_f32_e32 v250, v250, v55
	v_exp_f32_e32 v57, v1
	v_sub_f32_e32 v1, v60, v129
	v_add_f32_e32 v251, v251, v57
	v_exp_f32_e32 v58, v1
	s_waitcnt lgkmcnt(4)
	v_add_f32_e32 v252, v252, v58
	v_mfma_f32_32x32x16_bf16 v[16:31], v[108:111], v[48:51], v[16:31]
	v_cvt_pk_bf16_f32 v48, v78, v158
	v_cvt_pk_bf16_f32 v49, v79, v159
	v_cvt_pk_bf16_f32 v50, v52, v160
	v_cvt_pk_bf16_f32 v51, v53, v161
	v_sub_f32_e32 v1, v61, v129
	v_exp_f32_e32 v60, v1
	v_sub_f32_e32 v1, v62, v129
	v_add_f32_e32 v253, v253, v60
	s_waitcnt lgkmcnt(3)
	v_mfma_f32_32x32x16_bf16 v[32:47], v[104:107], v[48:51], v[32:47]
	v_exp_f32_e32 v59, v1
	v_sub_f32_e32 v1, v63, v129
	v_add_f32_e32 v254, v254, v59
	v_exp_f32_e32 v61, v1
	s_waitcnt lgkmcnt(2)
	v_add_f32_e32 v255, v255, v61
	v_mfma_f32_32x32x16_bf16 v[16:31], v[10:13], v[48:51], v[16:31]
	v_cvt_pk_bf16_f32 v10, v54, v56
	v_cvt_pk_bf16_f32 v11, v55, v57
	v_cvt_pk_bf16_f32 v12, v58, v60
	v_cvt_pk_bf16_f32 v13, v59, v61
	s_waitcnt lgkmcnt(1)
	s_nop 0
	v_mfma_f32_32x32x16_bf16 v[32:47], v[6:9], v[10:13], v[32:47]
	s_nop 0
	s_waitcnt lgkmcnt(0)
	v_mfma_f32_32x32x16_bf16 v[16:31], v[2:5], v[10:13], v[16:31]

; DI u32x2 pk4(float a, float b, float c, float d) { u32x2 r; r.x = pk2(a, b); r.y = pk2(c, d); return r; }
;     ...
;     { const auto sw = __builtin_amdgcn_permlane32_swap(__float_as_uint(lsum), __float_as_uint(lsum), false, false);
;       lsum = __uint_as_float(sw[0]) + __uint_as_float(sw[1]); }
;     const float inv = 1.0f / lsum;
;     {
;         unsigned char* sb = lds + 2 * STG + wid * (32 * 144);
; #pragma unroll
;         for (int d = 0; d < 2; ++d)
; #pragma unroll
;             for (int g = 0; g < 4; ++g)
;                 *(u32x2*)(sb + ln * 144 + (d * 32 + 8 * g + 4 * h) * 2) = pk4(o[d][4 * g] * inv, o[d][4 * g + 1] * inv, o[d][4 * g + 2] * inv, o[d][4 * g + 3] * inv);
;         __builtin_amdgcn_fence(__ATOMIC_RELEASE, "wavefront");
;         __builtin_amdgcn_wave_barrier();
;         __builtin_amdgcn_fence(__ATOMIC_ACQUIRE, "wavefront");
; #pragma unroll
;         for (int ps = 0; ps < 4; ++ps) {
;             const int row = ps * 8 + (lane >> 3), ch = lane & 7;
;             const u32x4 v = *(const u32x4*)(sb + row * 144 + ch * 16);
;             *(u32x4*)(obase + (size_t)(qw0 + row) * ldo + ch * 8) = v;
;         }
.LBB0_820:
	v_mov_b32_e32 v14, v0
	v_mov_b32_e32 v15, v0
	v_mov_b32_e32 v1, v0
	v_mov_b32_e32 v2, v0
	v_mov_b32_e32 v3, v0
	v_mov_b32_e32 v4, v0
	v_mov_b32_e32 v5, v0
	v_mov_b32_e32 v6, v0
	v_mov_b32_e32 v7, v0
	v_mov_b32_e32 v8, v0
	v_mov_b32_e32 v9, v0
	v_mov_b32_e32 v10, v0
	v_mov_b32_e32 v11, v0
	v_mov_b32_e32 v12, v0
	v_mov_b32_e32 v13, v0
	v_mov_b64_e32 v[30:31], v[14:15]
	v_mov_b64_e32 v[46:47], v[14:15]
	v_mov_b32_e32 v132, 0
	v_mov_b32_e32 v248, 0
	v_mov_b32_e32 v249, 0
	v_mov_b32_e32 v250, 0
	v_mov_b32_e32 v251, 0
	v_mov_b32_e32 v252, 0
	v_mov_b32_e32 v253, 0
	v_mov_b32_e32 v254, 0
	v_mov_b32_e32 v255, 0
	v_mov_b64_e32 v[28:29], v[12:13]
	v_mov_b64_e32 v[26:27], v[10:11]
	v_mov_b64_e32 v[24:25], v[8:9]
	v_mov_b64_e32 v[22:23], v[6:7]
	v_mov_b64_e32 v[20:21], v[4:5]
	v_mov_b64_e32 v[18:19], v[2:3]
	v_mov_b64_e32 v[16:17], v[0:1]
	v_mov_b64_e32 v[44:45], v[12:13]
	v_mov_b64_e32 v[42:43], v[10:11]
	v_mov_b64_e32 v[40:41], v[8:9]
	v_mov_b64_e32 v[38:39], v[6:7]
	v_mov_b64_e32 v[36:37], v[4:5]
	v_mov_b64_e32 v[34:35], v[2:3]
	v_mov_b64_e32 v[32:33], v[0:1]
.LBB0_821:
	v_add_f32_e32 v248, v248, v249
	v_add_f32_e32 v250, v250, v251
	v_add_f32_e32 v252, v252, v253
	v_add_f32_e32 v254, v254, v255
	v_add_f32_e32 v248, v248, v250
	v_add_f32_e32 v252, v252, v254
	v_add_f32_e32 v132, v248, v252
	v_mov_b32_e32 v1, v132
	s_nop 1
	v_permlane32_swap_b32_e32 v132, v1
	v_add_f32_e32 v1, v132, v1
	v_div_scale_f32 v2, s[18:19], v1, v1, 1.0
	v_rcp_f32_e32 v3, v2
	s_barrier
	v_fma_f32 v4, -v2, v3, 1.0
	v_fmac_f32_e32 v3, v4, v3
	v_div_scale_f32 v4, vcc, 1.0, v1, 1.0
	v_mul_f32_e32 v5, v4, v3
	v_fma_f32 v6, -v2, v5, v4
	v_fmac_f32_e32 v5, v6, v3
	v_fma_f32 v2, -v2, v5, v4
	v_div_fmas_f32 v2, v2, v3, v5
	v_div_fixup_f32 v2, v2, v1, 1.0
	v_pk_mul_f32 v[4:5], v[32:33], v[2:3] op_sel_hi:[1,0]
	v_pk_mul_f32 v[6:7], v[34:35], v[2:3] op_sel_hi:[1,0]
	v_cvt_pk_bf16_f32 v4, v4, v5
	v_cvt_pk_bf16_f32 v5, v6, v7
	v_add_u32_e32 v1, v174, v146
	v_pk_mul_f32 v[6:7], v[36:37], v[2:3] op_sel_hi:[1,0]
	v_pk_mul_f32 v[8:9], v[38:39], v[2:3] op_sel_hi:[1,0]
	v_cvt_pk_bf16_f32 v6, v6, v7
	v_cvt_pk_bf16_f32 v7, v8, v9
	v_add_u32_e32 v1, 0x9000, v1
	ds_write2_b64 v1, v[4:5], v[6:7] offset0:192 offset1:194
	v_pk_mul_f32 v[4:5], v[40:41], v[2:3] op_sel_hi:[1,0]
	v_pk_mul_f32 v[6:7], v[42:43], v[2:3] op_sel_hi:[1,0]
	v_cvt_pk_bf16_f32 v4, v4, v5
	v_cvt_pk_bf16_f32 v5, v6, v7
	v_pk_mul_f32 v[6:7], v[44:45], v[2:3] op_sel_hi:[1,0]
	v_pk_mul_f32 v[8:9], v[46:47], v[2:3] op_sel_hi:[1,0]
	v_cvt_pk_bf16_f32 v6, v6, v7
	v_cvt_pk_bf16_f32 v7, v8, v9
	ds_write2_b64 v1, v[4:5], v[6:7] offset0:196 offset1:198
	v_pk_mul_f32 v[4:5], v[16:17], v[2:3] op_sel_hi:[1,0]
	v_pk_mul_f32 v[6:7], v[18:19], v[2:3] op_sel_hi:[1,0]
	v_cvt_pk_bf16_f32 v4, v4, v5
	v_cvt_pk_bf16_f32 v5, v6, v7
	v_pk_mul_f32 v[6:7], v[20:21], v[2:3] op_sel_hi:[1,0]
	v_pk_mul_f32 v[8:9], v[22:23], v[2:3] op_sel_hi:[1,0]
	v_cvt_pk_bf16_f32 v6, v6, v7
	v_cvt_pk_bf16_f32 v7, v8, v9
	ds_write2_b64 v1, v[4:5], v[6:7] offset0:200 offset1:202
	v_pk_mul_f32 v[4:5], v[24:25], v[2:3] op_sel_hi:[1,0]
	v_pk_mul_f32 v[6:7], v[26:27], v[2:3] op_sel_hi:[1,0]
	v_cvt_pk_bf16_f32 v4, v4, v5
	v_cvt_pk_bf16_f32 v5, v6, v7
	v_pk_mul_f32 v[6:7], v[28:29], v[2:3] op_sel_hi:[1,0]
	v_pk_mul_f32 v[2:3], v[30:31], v[2:3] op_sel_hi:[1,0]
	v_cvt_pk_bf16_f32 v6, v6, v7
	v_cvt_pk_bf16_f32 v7, v2, v3
	ds_write2_b64 v1, v[4:5], v[6:7] offset0:204 offset1:206
	v_add_u32_e32 v1, v175, v187
	ds_read_b128 v[2:5], v1 offset:38400
	v_or_b32_e32 v8, v209, v167
	v_ashrrev_i32_e32 v9, 31, v8
	v_lshl_add_u64 v[6:7], v[142:143], 1, s[68:69]
	v_lshlrev_b64 v[8:9], 11, v[8:9]
	v_lshl_add_u64 v[6:7], v[6:7], 0, v[8:9]
	s_mov_b64 s[18:19], 0
	s_waitcnt lgkmcnt(0)
	global_store_dwordx4 v[6:7], v[2:5], off
